# attention item prologue: four Q chunk loads issued together and converted in place with counted waits (three exposed load latencies removed per item)
# baseline (speedup 1.0000x reference)
; #define LAS __attribute__((address_space(3)))
; #define OPQV(x) asm volatile("" : "+v"(x))
; DEV void unpack8(const u32x4 v, float (&f)[8]) { f[0] = bflo(v.x); f[1] = bfhi(v.x); f[2] = bflo(v.y); f[3] = bfhi(v.y); f[4] = bflo(v.z); f[5] = bfhi(v.z); f[6] = bflo(v.w); f[7] = bfhi(v.w); }
; DEV u32x4 pack8(const float (&f)[8]) { u32x4 w; w.x = cvt_pk_bf16(f[0], f[1]); w.y = cvt_pk_bf16(f[2], f[3]); w.z = cvt_pk_bf16(f[4], f[5]); w.w = cvt_pk_bf16(f[6], f[7]); return w; }
; DEV void attn_item(LAS unsigned char* lds, const bf16_t* P, const bf16_t* QB, const bf16_t* KV, const bf16_t* KC, const bf16_t* VC, const float* rel_bias, bf16_t* OB, int b, int g, int qt) {
;     ...
;     const int lane = tid & 63, wave = tid >> 6, fr = lane & 15, g4 = lane >> 4;
;     const int qs = wave >> 1, hp = wave & 1;
;     const int tl = qt * 64 + qs * 16 + fr;
;     const size_t tok = (size_t)b * S_ + tl;
;     unsigned kb = AT_KS + (fr * 72 + g4 * 8) * 2, vb1 = AT_VT + (fr * 72 + g4 * 4) * 2, vb2 = AT_VT + (fr * 136 + g4 * 4) * 2, btb = AT_BT + hp * 1032;
;     OPQV(kb); OPQV(vb1); OPQV(vb2); OPQV(btb);
;     LAS float* BT = (LAS float*)(lds + AT_BT);
;     const LAS int* BK = (const LAS int*)(lds + AT_BK);
;     LAS float* IA = (LAS float*)(lds + AT_IMP);
;     LAS float* IB = (LAS float*)(lds + AT_IMP + 16384);
;     LAS unsigned* MASK = (LAS unsigned*)(lds + AT_MASK);
;     bf16x8 qf[2][2];
; #pragma unroll
;     for (int hh = 0; hh < 2; ++hh)
; #pragma unroll
;         for (int ks = 0; ks < 2; ++ks) { float qv[8]; unpack8(*(const u32x4*)(QB + tok * 1024 + (g * 4 + hp * 2 + hh) * 64 + ks * 32 + g4 * 8), qv);
; #pragma unroll
;             for (int e = 0; e < 8; ++e) qv[e] *= QSC_;
;             qf[hh][ks] = as_bf16x8(pack8(qv)); }
.LBB0_167:
	s_andn2_b64 vcc, exec, s[4:5]
	s_cbranch_vccnz .LBB0_158
	v_mov_b32_e32 v150, v210
	s_ashr_i32 s17, s43, 5
	s_sub_i32 s15, 31, s17
	v_ashrrev_i32_e32 v44, 3, v150
	v_and_b32_e32 v137, -16, v44
	v_and_b32_e32 v136, 15, v150
	v_lshl_add_u32 v0, s15, 6, v137
	v_bfe_u32 v33, v150, 4, 2
	v_or_b32_e32 v6, v0, v136
	v_mul_u32_u24_e32 v0, 0x48, v136
	s_lshl_b32 s4, s43, 9
	v_lshl_add_u32 v0, v33, 3, v0
	v_lshlrev_b32_e32 v138, 2, v33
	v_ashrrev_i32_e32 v146, 6, v150
	s_and_b32 s36, s4, 0x3800
	v_ashrrev_i32_e32 v7, 31, v6
	v_lshlrev_b32_e32 v34, 1, v0
	v_sub_u32_e32 v0, v0, v138
	s_and_b32 s42, s43, 3
	v_and_b32_e32 v151, 1, v146
	s_waitcnt vmcnt(9)
	v_lshl_add_u64 v[24:25], v[6:7], 0, s[36:37]
	v_lshl_add_u32 v145, v0, 1, v221
	v_lshl_add_u32 v0, v136, 6, v0
	v_lshl_add_u32 v32, v0, 1, v221
	v_mul_u32_u24_e32 v0, 0x408, v151
	v_lshlrev_b64 v[96:97], 11, v[24:25]
	s_lshl_b32 s4, s42, 2
	v_or_b32_e32 v35, 0x9000, v0
	v_lshl_add_u64 v[2:3], s[78:79], 0, v[96:97]
	v_lshl_or_b32 v36, v151, 1, s4
	v_and_b32_e32 v0, 48, v150
	v_lshl_add_u64 v[2:3], v[2:3], 0, v[0:1]
	v_lshlrev_b32_e32 v0, 7, v36
	v_lshl_add_u64 v[20:21], v[2:3], 0, v[0:1]
	global_load_dwordx4 v[8:11], v[20:21], off
	global_load_dwordx4 v[12:15], v[20:21], off offset:64
	global_load_dwordx4 v[16:19], v[20:21], off offset:128
	global_load_dwordx4 v[20:23], v[20:21], off offset:192
	s_lshl_b32 s36, s42, 3
	v_lshlrev_b32_e32 v98, 3, v150
	v_ashrrev_i32_e32 v99, 31, v98
	v_and_b32_e32 v100, -8, v44
	v_ashrrev_i32_e32 v101, 31, v100
	v_and_b32_e32 v37, 56, v98
	v_lshlrev_b32_e32 v38, 6, v44
	v_ashrrev_i32_e32 v39, 31, v38
	v_lshlrev_b64 v[42:43], 1, v[38:39]
	s_movk_i32 s24, 0x48
	s_waitcnt vmcnt(3)
	v_lshlrev_b32_e32 v0, 16, v8
	v_and_b32_e32 v2, 0xffff0000, v8
	v_lshlrev_b32_e32 v7, 16, v9
	v_and_b32_e32 v3, 0xffff0000, v9
	v_and_b32_e32 v4, 0xffff0000, v10
	v_lshlrev_b32_e32 v10, 16, v10
	v_and_b32_e32 v5, 0xffff0000, v11
	v_lshlrev_b32_e32 v11, 16, v11
	v_mul_f32_e32 v0, 0x3e38aa3b, v0
	v_mul_f32_e32 v2, 0x3e38aa3b, v2
	v_mul_f32_e32 v7, 0x3e38aa3b, v7
	v_mul_f32_e32 v3, 0x3e38aa3b, v3
	v_mul_f32_e32 v10, 0x3e38aa3b, v10
	v_mul_f32_e32 v4, 0x3e38aa3b, v4
	v_mul_f32_e32 v11, 0x3e38aa3b, v11
	v_mul_f32_e32 v5, 0x3e38aa3b, v5
	v_cvt_pk_bf16_f32 v8, v0, v2
	v_cvt_pk_bf16_f32 v9, v7, v3
	v_cvt_pk_bf16_f32 v10, v10, v4
	v_cvt_pk_bf16_f32 v11, v11, v5
	s_waitcnt vmcnt(2)
	v_lshlrev_b32_e32 v0, 16, v12
	v_and_b32_e32 v2, 0xffff0000, v12
	v_lshlrev_b32_e32 v7, 16, v13
	v_and_b32_e32 v3, 0xffff0000, v13
	v_and_b32_e32 v4, 0xffff0000, v14
	v_lshlrev_b32_e32 v14, 16, v14
	v_and_b32_e32 v5, 0xffff0000, v15
	v_lshlrev_b32_e32 v15, 16, v15
	v_mul_f32_e32 v0, 0x3e38aa3b, v0
	v_mul_f32_e32 v2, 0x3e38aa3b, v2
	v_mul_f32_e32 v7, 0x3e38aa3b, v7
	v_mul_f32_e32 v3, 0x3e38aa3b, v3
	v_mul_f32_e32 v14, 0x3e38aa3b, v14
	v_mul_f32_e32 v4, 0x3e38aa3b, v4
	v_mul_f32_e32 v15, 0x3e38aa3b, v15
	v_mul_f32_e32 v5, 0x3e38aa3b, v5
	v_cvt_pk_bf16_f32 v12, v0, v2
	v_cvt_pk_bf16_f32 v13, v7, v3
	v_cvt_pk_bf16_f32 v14, v14, v4
	v_cvt_pk_bf16_f32 v15, v15, v5
	s_waitcnt vmcnt(1)
	v_lshlrev_b32_e32 v0, 16, v16
	v_and_b32_e32 v2, 0xffff0000, v16
	v_lshlrev_b32_e32 v7, 16, v17
	v_and_b32_e32 v3, 0xffff0000, v17
	v_and_b32_e32 v4, 0xffff0000, v18
	v_lshlrev_b32_e32 v18, 16, v18
	v_and_b32_e32 v5, 0xffff0000, v19
	v_lshlrev_b32_e32 v19, 16, v19
	v_mul_f32_e32 v0, 0x3e38aa3b, v0
	v_mul_f32_e32 v2, 0x3e38aa3b, v2
	v_mul_f32_e32 v7, 0x3e38aa3b, v7
	v_mul_f32_e32 v3, 0x3e38aa3b, v3
	v_mul_f32_e32 v18, 0x3e38aa3b, v18
	v_mul_f32_e32 v4, 0x3e38aa3b, v4
	v_mul_f32_e32 v19, 0x3e38aa3b, v19
	v_mul_f32_e32 v5, 0x3e38aa3b, v5
	v_cvt_pk_bf16_f32 v16, v0, v2
	v_cvt_pk_bf16_f32 v17, v7, v3
	v_cvt_pk_bf16_f32 v18, v18, v4
	v_cvt_pk_bf16_f32 v19, v19, v5
	s_waitcnt vmcnt(0)
; #define LAS __attribute__((address_space(3)))
; #define OPQV(x) asm volatile("" : "+v"(x))
; DEV float bf2f(unsigned b) { return __uint_as_float(b << 16); }
; DEV void unpack8(const u32x4 v, float (&f)[8]) { f[0] = bflo(v.x); f[1] = bfhi(v.x); f[2] = bflo(v.y); f[3] = bfhi(v.y); f[4] = bflo(v.z); f[5] = bfhi(v.z); f[6] = bflo(v.w); f[7] = bfhi(v.w); }
; DEV void attn_item(LAS unsigned char* lds, const bf16_t* P, const bf16_t* QB, const bf16_t* KV, const bf16_t* KC, const bf16_t* VC, const float* rel_bias, bf16_t* OB, int b, int g, int qt) {
;     ...
;         for (int ks = 0; ks < 2; ++ks) { float qv[8]; unpack8(*(const u32x4*)(QB + tok * 1024 + (g * 4 + hp * 2 + hh) * 64 + ks * 32 + g4 * 8), qv);
; #pragma unroll
;             for (int e = 0; e < 8; ++e) qv[e] *= QSC_;
;             qf[hh][ks] = as_bf16x8(pack8(qv)); }
;     float gate[3][2];
; #pragma unroll
;     for (int br = 0; br < 3; ++br)
; #pragma unroll
;         for (int hh = 0; hh < 2; ++hh) gate[br][hh] = bf2f(P[tok * NP + COL_GN + br * 16 + g * 4 + hp * 2 + hh]);
;     f32x4 F[2][4];
; #pragma unroll
;     for (int hh = 0; hh < 2; ++hh)
; #pragma unroll
;         for (int dt = 0; dt < 4; ++dt) F[hh][dt] = (f32x4){0.f, 0.f, 0.f, 0.f};
;     const bf16_t* pbg = KV + (size_t)(b * 4 + g) * S_ * 64;
;     KVRegs pre = kv_fetch(pbg + 2 * KV_TENSOR, pbg + 3 * KV_TENSOR, tid);
;     {
;         const bf16_t* kc = KC + (size_t)(b * 4 + g) * 128 * 64; const bf16_t* vc = VC + (size_t)(b * 4 + g) * 128 * 64;
; #pragma unroll
;         for (int it = 0; it < 2; ++it) { const int idx = it * 512 + tid, key = idx >> 3, c8 = (idx & 7) * 8;
;             const u32x4 kv = *(const u32x4*)(kc + key * 64 + c8); const u32x4 vv = *(const u32x4*)(vc + key * 64 + c8);
;             unsigned kw = AT_KS + (key * 72 + c8) * 2, vw = AT_VT + (c8 * 136 + key) * 2; OPQV(kw); OPQV(vw);
;             *(LAS u32x4*)(lds + kw) = kv;
; #pragma unroll
;             for (int j = 0; j < 4; ++j) { *(LAS bf16_t*)(lds + vw + j * 544) = (bf16_t)(vv[j] & 0xffffu); *(LAS bf16_t*)(lds + vw + j * 544 + 272) = (bf16_t)(vv[j] >> 16); } }
;         for (int e = tid; e < 4 * 129; e += 512) { const int r = e / 129, idx = e - r * 129; BT[e] = LOG2E_ * *(const LAS float*)(lds + AT_RB + (BK[idx] * 16 + g * 4 + r) * 4); }
	v_lshlrev_b32_e32 v0, 16, v20
	v_and_b32_e32 v2, 0xffff0000, v20
	v_lshlrev_b32_e32 v7, 16, v21
	v_and_b32_e32 v3, 0xffff0000, v21
	v_and_b32_e32 v4, 0xffff0000, v22
	v_lshlrev_b32_e32 v22, 16, v22
	v_and_b32_e32 v5, 0xffff0000, v23
	v_lshlrev_b32_e32 v23, 16, v23
	v_mul_f32_e32 v0, 0x3e38aa3b, v0
	v_mul_f32_e32 v2, 0x3e38aa3b, v2
	v_mul_f32_e32 v7, 0x3e38aa3b, v7
	v_mul_f32_e32 v3, 0x3e38aa3b, v3
	v_mul_f32_e32 v22, 0x3e38aa3b, v22
	v_mul_f32_e32 v4, 0x3e38aa3b, v4
	v_mul_f32_e32 v23, 0x3e38aa3b, v23
	v_mul_f32_e32 v5, 0x3e38aa3b, v5
	v_cvt_pk_bf16_f32 v20, v0, v2
	v_cvt_pk_bf16_f32 v21, v7, v3
	v_cvt_pk_bf16_f32 v22, v22, v4
	v_cvt_pk_bf16_f32 v23, v23, v5
	v_mov_b64_e32 v[2:3], s[76:77]
	v_mad_u64_u32 v[2:3], s[4:5], v24, s59, v[2:3]
	v_mad_i32_i24 v3, v25, s59, v3
	v_lshl_add_u64 v[2:3], v[2:3], 0, s[36:37]
	v_lshlrev_b32_e32 v0, 2, v151
	v_lshl_add_u64 v[2:3], v[2:3], 0, v[0:1]
	s_mov_b64 s[4:5], 0x5400
	v_lshl_add_u64 v[4:5], v[2:3], 0, s[4:5]
	s_movk_i32 s4, 0x5000
	v_add_co_u32_e32 v2, vcc, s4, v2
	s_and_b32 s4, s43, 31
	s_lshl_b32 s5, s4, 18
	s_add_u32 s90, s70, s5
	v_addc_co_u32_e32 v3, vcc, 0, v3, vcc
	s_addc_u32 s91, s8, 0
	global_load_dword v149, v[2:3], off offset:1024
	global_load_dword v148, v[4:5], off offset:32
	global_load_dword v147, v[4:5], off offset:64
	v_lshl_add_u64 v[2:3], v[98:99], 1, s[90:91]
	s_mov_b32 s5, 0x1000000
	v_lshlrev_b32_e32 v0, 6, v150
	v_add_co_u32_e32 v2, vcc, s5, v2
	v_and_b32_e32 v0, 0xfc0, v0
	s_nop 0
	v_addc_co_u32_e32 v3, vcc, 0, v3, vcc
	v_lshlrev_b32_e32 v0, 1, v0
	global_load_dwordx4 v[24:27], v[2:3], off
	v_lshl_add_u64 v[2:3], s[90:91], 0, v[0:1]
	s_lshl_b32 s6, s4, 14
	v_lshl_add_u64 v[2:3], v[100:101], 1, v[2:3]
	s_mov_b32 s5, 0x1800000
	s_add_u32 s4, s12, s6
	v_add_co_u32_e32 v2, vcc, s5, v2
	s_addc_u32 s5, s13, 0
	s_nop 0
	v_addc_co_u32_e32 v3, vcc, 0, v3, vcc
	s_add_u32 s6, s20, s6
	global_load_dwordx4 v[28:31], v[2:3], off
	s_addc_u32 s7, s21, 0
	v_lshlrev_b32_e32 v2, 1, v37
	v_mov_b32_e32 v3, v1
	v_lshl_add_u64 v[4:5], s[4:5], 0, v[2:3]
	v_lshl_add_u64 v[2:3], s[6:7], 0, v[2:3]
	s_movk_i32 s5, 0x48
	v_lshl_add_u64 v[38:39], v[4:5], 0, v[42:43]
	v_lshl_add_u64 v[42:43], v[2:3], 0, v[42:43]
	v_mul_lo_u32 v7, v44, s5
	s_movk_i32 s4, 0x88
	global_load_dwordx4 v[38:41], v[38:39], off
	v_add_lshl_u32 v139, v7, v37, 1
	v_mad_u32_u24 v7, v37, s4, v44
	global_load_dwordx4 v[42:45], v[42:43], off
	v_lshl_add_u32 v7, v7, 1, v221
	v_mov_b32_e32 v46, v139
	v_cmp_gt_i32_e32 vcc, s96, v150
	v_add_u32_e32 v46, 0, v46
	v_add_u32_e32 v7, 0, v7
	s_waitcnt vmcnt(1)
	ds_write_b128 v46, v[38:41]
	s_waitcnt vmcnt(0)
	ds_write_b16 v7, v42
	ds_write_b16_d16_hi v7, v42 offset:272
	ds_write_b16 v7, v43 offset:544
	ds_write_b16_d16_hi v7, v43 offset:816
	ds_write_b16 v7, v44 offset:1088
	ds_write_b16_d16_hi v7, v44 offset:1360
	ds_write_b16 v7, v45 offset:1632
	ds_write_b16_d16_hi v7, v45 offset:1904
	v_add_u32_e32 v7, 0x200, v150
	v_ashrrev_i32_e32 v44, 3, v7
	v_lshlrev_b32_e32 v38, 6, v44
	v_ashrrev_i32_e32 v39, 31, v38
	v_lshlrev_b64 v[42:43], 1, v[38:39]
	v_lshl_add_u64 v[4:5], v[4:5], 0, v[42:43]
	global_load_dwordx4 v[38:41], v[4:5], off
	v_mul_lo_u32 v4, v44, s5
	v_lshl_add_u64 v[2:3], v[2:3], 0, v[42:43]
	v_add_lshl_u32 v42, v4, v37, 1
	v_mad_u32_u24 v4, v37, s4, v44
	v_lshl_add_u32 v37, v4, 1, v221
	global_load_dwordx4 v[2:5], v[2:3], off
	s_nop 0
	v_add_u32_e32 v42, 0, v42
	v_add_u32_e32 v37, 0, v37
	s_waitcnt vmcnt(1)
	ds_write_b128 v42, v[38:41]
	s_waitcnt vmcnt(0)
	ds_write_b16 v37, v2
	ds_write_b16_d16_hi v37, v2 offset:272
	ds_write_b16 v37, v3 offset:544
	ds_write_b16_d16_hi v37, v3 offset:816
	ds_write_b16 v37, v4 offset:1088
	ds_write_b16_d16_hi v37, v4 offset:1360
	ds_write_b16 v37, v5 offset:1632
	ds_write_b16_d16_hi v37, v5 offset:1904
	s_and_saveexec_b64 s[4:5], vcc
	s_cbranch_execz .LBB0_171
	s_lshl_b32 s6, s42, 4
	s_add_i32 s36, s6, 0
	s_add_i32 s6, 0, 0x9000
	s_add_i32 s36, s36, 0x13d00
	v_lshl_add_u32 v2, v150, 2, s6
	s_mov_b64 s[6:7], 0
	v_mov_b32_e32 v3, v150
